# P5 K-loop: each workgroup warms its share of the shared A / B K-tile lines in L2 three K-tiles ahead (one dword load per wave per K-tile), counted waits 10/9/10/9
# speedup vs baseline: 1.0182x; 1.0182x over previous
; #define PG8_STAGE(bufoff, gbase, voff) do { _Pragma("unroll") for (int _i = 0; _i < 2; ++_i) \
;         __builtin_amdgcn_global_load_lds((const unsigned*)((const char*)(gbase) + (voff)[_i]), (PG8_LAS unsigned*)(lds + (bufoff) + ldsw + _i * 8192), 16, 0, 0); } while (0)
; #define PG8_LDA(dst, b, h) do { _Pragma("unroll") for (int m = 0; m < 4; ++m) _Pragma("unroll") for (int k = 0; k < 2; ++k) dst[m][k] = *(const PG8_LAS bf16x8*)(lds + PG8_SA(b, h) + aoff + m * 2048 + k * 1024); } while (0)
; #define PG8_LDB(dst, b, h) do { _Pragma("unroll") for (int n = 0; n < 2; ++n) _Pragma("unroll") for (int k = 0; k < 2; ++k) dst[n][k] = *(const PG8_LAS bf16x8*)(lds + PG8_SB(b, h) + boff + n * 2048 + k * 1024); } while (0)
; #define PG8_MMA(ai, bj, At, Bt) do { __builtin_amdgcn_s_setprio(1); _Pragma("unroll") for (int m = 0; m < 4; ++m) _Pragma("unroll") for (int n = 0; n < 2; ++n) _Pragma("unroll") for (int k = 0; k < 2; ++k) \
;         acc[ai][bj][m][n] = __builtin_amdgcn_mfma_f32_16x16x32_bf16(Bt[n][k], At[m][k], acc[ai][bj][m][n], 0, 0, 0); __builtin_amdgcn_s_setprio(0); } while (0)
; #define PG8_WAIT_V(n) asm volatile("s_waitcnt vmcnt(" #n ")" ::: "memory")
; #define PG8_WAIT_L(n) asm volatile("s_waitcnt lgkmcnt(" #n ")" ::: "memory")
; #define PG8_BAR __builtin_amdgcn_s_barrier()
; #define PG8_SCHED __builtin_amdgcn_sched_barrier(0)
; template <class Epi, class Sched, bool ALIGN_EPI = false, bool SP2 = false>
; __device__ __forceinline__ void gemm_phase(PG8_LAS unsigned char* lds, const Gemm g, const Sched& S, const Epi& E) {
;     ...
;         for (int t = 0; t < nt; t += 2) {
;             const bool last = (t == nt - 2);
;             const char* a1 = cA + (size_t)(t + 1) * kstep;
;             const char* a2 = last ? nA : cA + (size_t)(t + 2) * kstep; const char* b2 = last ? nB : cB + (size_t)(t + 2) * kstep;
;             const char* a3 = a2 + kstep; const char* b3 = b2 + kstep;
;             if (last && has_next) S.a_ready(nxt);
;             if constexpr (SP2) {
;             PG8_LDB(B0, 0, 0); PG8_LDB(B1, 0, 1); PG8_SCHED; PG8_LDA(At, 0, 0); PG8_STAGE(PG8_SA(1, 1), a1 + hstep, voffA);
;             PG8_WAIT_V(8); PG8_WAIT_L(0); PG8_BAR; PG8_MMA(0, 0, At, B0); PG8_MMA(0, 1, At, B1); PG8_BAR; PG8_SCHED;
.LBB0_1423:
	s_add_u32 s12, s12, 0xb4000
	s_addc_u32 s13, s13, 0
	s_add_u32 s36, s36, 0x8000
	s_addc_u32 s37, s37, 0
	s_mov_b32 s57, -2
	s_lshr_b32 s58, s96, 6
	s_bfe_u32 s59, s96, 0x30003
	s_lshr_b32 s60, s58, 1
	s_mul_i32 s60, s60, 0xb0000
	s_and_b32 s61, s58, 1
	s_lshl_b32 s61, s61, 13
	s_add_i32 s60, s60, s61
	s_lshr_b32 s61, s59, 2
	s_mul_i32 s61, s61, 0xb0000
	s_and_b32 s97, s59, 3
	s_lshl_b32 s97, s97, 12
	s_add_i32 s61, s61, s97
	s_add_u32 s58, s12, 0xfff54000
	s_addc_u32 s59, s13, -1
	s_add_u32 s58, s58, s60
	s_addc_u32 s59, s59, 0
	s_add_u32 s60, s36, s61
	s_addc_u32 s61, s37, 0
	s_cmp_lg_u64 s[28:29], 0
	s_cselect_b32 s98, s58, s60
	s_cselect_b32 s99, s59, s61
	s_cselect_b32 s97, 6, 7
	s_cselect_b32 s100, 63, 31
	v_lshrrev_b32_e32 v214, s97, v128
	v_and_b32_e32 v214, s100, v214
	v_lshlrev_b32_e32 v214, 7, v214
	v_mov_b32_e32 v215, 0
	v_lshl_add_u64 v[214:215], s[98:99], 0, v[214:215]
	global_load_dword v250, v[214:215], off
	v_lshl_add_u64 v[214:215], v[214:215], 0, s[20:21]
	global_load_dword v250, v[214:215], off
	v_lshl_add_u64 v[214:215], v[214:215], 0, s[20:21]
	global_load_dword v250, v[214:215], off
	v_lshl_add_u64 v[214:215], v[214:215], 0, s[20:21]
	ds_read_b128 v[136:139], v143
	ds_read_b128 v[146:149], v143 offset:1024
	ds_read_b128 v[150:153], v143 offset:2048
	ds_read_b128 v[154:157], v143 offset:3072
	ds_read_b128 v[158:161], v144
	ds_read_b128 v[162:165], v144 offset:1024
	ds_read_b128 v[166:169], v144 offset:2048
	ds_read_b128 v[170:173], v144 offset:3072
	s_add_u32 s58, s12, 0xfff54000
	s_addc_u32 s59, s13, -1
	s_cmp_eq_u32 s57, 40
	s_cselect_b32 s59, s3, s59
	s_cselect_b32 s58, s2, s58
	s_cselect_b32 s61, s35, s37
	s_cselect_b32 s60, s34, s36
	v_lshl_add_u64 v[198:199], s[12:13], 0, v[128:129]
	s_add_i32 m0, s39, 0xc000
	ds_read_b128 v[174:177], v145
	ds_read_b128 v[178:181], v145 offset:1024
	ds_read_b128 v[182:185], v145 offset:2048
	ds_read_b128 v[186:189], v145 offset:3072
	ds_read_b128 v[190:193], v145 offset:4096
	ds_read_b128 v[194:197], v145 offset:5120
	ds_read_b128 v[202:205], v145 offset:6144
	ds_read_b128 v[206:209], v145 offset:7168
	global_load_lds_dwordx4 v[198:199], off
	v_lshl_add_u64 v[198:199], v[198:199], 0, s[10:11]
	s_add_i32 m0, s39, 0xe000
	s_nop 0
	global_load_lds_dwordx4 v[198:199], off
	global_load_dword v250, v[214:215], off
	v_lshl_add_u64 v[214:215], v[214:215], 0, s[20:21]
	s_waitcnt vmcnt(10)
	s_waitcnt lgkmcnt(0)
	s_barrier
	s_setprio 1
	s_waitcnt lgkmcnt(0)
	v_mfma_f32_16x16x32_bf16 v[124:127], v[136:139], v[174:177], 0
	v_mfma_f32_16x16x32_bf16 v[120:123], v[150:153], v[174:177], 0
	v_mfma_f32_16x16x32_bf16 v[108:111], v[136:139], v[182:185], 0
	v_mfma_f32_16x16x32_bf16 v[104:107], v[150:153], v[182:185], 0
	v_mfma_f32_16x16x32_bf16 v[92:95], v[136:139], v[190:193], 0
	v_mfma_f32_16x16x32_bf16 v[88:91], v[150:153], v[190:193], 0
	v_mfma_f32_16x16x32_bf16 v[76:79], v[136:139], v[202:205], 0
	v_mfma_f32_16x16x32_bf16 v[72:75], v[150:153], v[202:205], 0
	v_mfma_f32_16x16x32_bf16 v[124:127], v[146:149], v[178:181], v[124:127]
	v_mfma_f32_16x16x32_bf16 v[120:123], v[154:157], v[178:181], v[120:123]
	v_mfma_f32_16x16x32_bf16 v[108:111], v[146:149], v[186:189], v[108:111]
	v_mfma_f32_16x16x32_bf16 v[104:107], v[154:157], v[186:189], v[104:107]
	v_mfma_f32_16x16x32_bf16 v[92:95], v[146:149], v[194:197], v[92:95]
	v_mfma_f32_16x16x32_bf16 v[88:91], v[154:157], v[194:197], v[88:91]
	v_mfma_f32_16x16x32_bf16 v[76:79], v[146:149], v[206:209], v[76:79]
	v_mfma_f32_16x16x32_bf16 v[72:75], v[154:157], v[206:209], v[72:75]
	s_setprio 0
	s_setprio 1
	v_mfma_f32_16x16x32_bf16 v[116:119], v[158:161], v[174:177], 0
	v_mfma_f32_16x16x32_bf16 v[112:115], v[166:169], v[174:177], 0
	v_mfma_f32_16x16x32_bf16 v[100:103], v[158:161], v[182:185], 0
	v_mfma_f32_16x16x32_bf16 v[96:99], v[166:169], v[182:185], 0
	v_mfma_f32_16x16x32_bf16 v[84:87], v[158:161], v[190:193], 0
	v_mfma_f32_16x16x32_bf16 v[80:83], v[166:169], v[190:193], 0
	v_mfma_f32_16x16x32_bf16 v[68:71], v[158:161], v[202:205], 0
	v_mfma_f32_16x16x32_bf16 v[64:67], v[166:169], v[202:205], 0
	v_mfma_f32_16x16x32_bf16 v[116:119], v[162:165], v[178:181], v[116:119]
	v_mfma_f32_16x16x32_bf16 v[112:115], v[170:173], v[178:181], v[112:115]
	v_mfma_f32_16x16x32_bf16 v[100:103], v[162:165], v[186:189], v[100:103]
	v_mfma_f32_16x16x32_bf16 v[96:99], v[170:173], v[186:189], v[96:99]
	v_mfma_f32_16x16x32_bf16 v[84:87], v[162:165], v[194:197], v[84:87]
	v_mfma_f32_16x16x32_bf16 v[80:83], v[170:173], v[194:197], v[80:83]
	v_mfma_f32_16x16x32_bf16 v[68:71], v[162:165], v[206:209], v[68:71]
	v_mfma_f32_16x16x32_bf16 v[64:67], v[170:173], v[206:209], v[64:67]
	s_setprio 0
	s_barrier
	v_lshl_add_u64 v[198:199], s[60:61], 0, v[128:129]
	s_add_i32 s60, s51, s38
	s_mov_b32 m0, s60
	ds_read_b128 v[174:177], v145 offset:16384
	ds_read_b128 v[178:181], v145 offset:17408
	ds_read_b128 v[182:185], v145 offset:18432
	ds_read_b128 v[186:189], v145 offset:19456
	ds_read_b128 v[190:193], v145 offset:20480
	ds_read_b128 v[194:197], v145 offset:21504
	ds_read_b128 v[202:205], v145 offset:22528
	ds_read_b128 v[206:209], v145 offset:23552
	global_load_lds_dwordx4 v[198:199], off
	v_lshl_add_u64 v[210:211], v[198:199], 0, s[10:11]
	s_add_i32 m0, s60, 0x2000
	s_add_i32 s60, s52, s38
	global_load_lds_dwordx4 v[210:211], off
	v_lshl_add_u64 v[210:211], v[198:199], 0, s[14:15]
	s_mov_b32 m0, s60
	s_nop 0
	global_load_lds_dwordx4 v[210:211], off
	v_lshl_add_u64 v[210:211], v[198:199], 0, s[16:17]
	s_add_i32 m0, s60, 0x2000
	s_nop 0
	global_load_lds_dwordx4 v[210:211], off
	v_lshl_add_u64 v[210:211], s[58:59], 0, v[128:129]
	s_mov_b32 m0, s39
	v_lshl_add_u64 v[212:213], v[210:211], 0, s[10:11]
	global_load_lds_dwordx4 v[210:211], off
	s_mov_b32 m0, s40
	s_nop 0
	global_load_lds_dwordx4 v[212:213], off
	s_waitcnt vmcnt(9)
	s_waitcnt lgkmcnt(0)
	s_barrier
; #define PG8_STAGE(bufoff, gbase, voff) do { _Pragma("unroll") for (int _i = 0; _i < 2; ++_i) \
;         __builtin_amdgcn_global_load_lds((const unsigned*)((const char*)(gbase) + (voff)[_i]), (PG8_LAS unsigned*)(lds + (bufoff) + ldsw + _i * 8192), 16, 0, 0); } while (0)
; #define PG8_LDA(dst, b, h) do { _Pragma("unroll") for (int m = 0; m < 4; ++m) _Pragma("unroll") for (int k = 0; k < 2; ++k) dst[m][k] = *(const PG8_LAS bf16x8*)(lds + PG8_SA(b, h) + aoff + m * 2048 + k * 1024); } while (0)
; #define PG8_LDB(dst, b, h) do { _Pragma("unroll") for (int n = 0; n < 2; ++n) _Pragma("unroll") for (int k = 0; k < 2; ++k) dst[n][k] = *(const PG8_LAS bf16x8*)(lds + PG8_SB(b, h) + boff + n * 2048 + k * 1024); } while (0)
; #define PG8_MMA(ai, bj, At, Bt) do { __builtin_amdgcn_s_setprio(1); _Pragma("unroll") for (int m = 0; m < 4; ++m) _Pragma("unroll") for (int n = 0; n < 2; ++n) _Pragma("unroll") for (int k = 0; k < 2; ++k) \
;         acc[ai][bj][m][n] = __builtin_amdgcn_mfma_f32_16x16x32_bf16(Bt[n][k], At[m][k], acc[ai][bj][m][n], 0, 0, 0); __builtin_amdgcn_s_setprio(0); } while (0)
; #define PG8_WAIT_V(n) asm volatile("s_waitcnt vmcnt(" #n ")" ::: "memory")
; #define PG8_WAIT_L(n) asm volatile("s_waitcnt lgkmcnt(" #n ")" ::: "memory")
; #define PG8_BAR __builtin_amdgcn_s_barrier()
; #define PG8_SCHED __builtin_amdgcn_sched_barrier(0)
; template <class Epi, class Sched, bool ALIGN_EPI = false, bool SP2 = false>
; __device__ __forceinline__ void gemm_phase(PG8_LAS unsigned char* lds, const Gemm g, const Sched& S, const Epi& E) {
;     ...
;             PG8_WAIT_V(8); PG8_WAIT_L(0); PG8_BAR; PG8_MMA(1, 0, At, B0); PG8_MMA(1, 1, At, B1); PG8_BAR; PG8_SCHED;
;             PG8_LDB(B0, 1, 0); PG8_LDB(B1, 1, 1); PG8_SCHED; PG8_LDA(At, 1, 0); PG8_STAGE(PG8_SA(0, 1), a2 + hstep, voffA);
;             PG8_WAIT_V(8); PG8_WAIT_L(0); PG8_BAR; PG8_MMA(0, 0, At, B0); PG8_MMA(0, 1, At, B1); PG8_BAR; PG8_SCHED;
	s_setprio 1
	s_waitcnt lgkmcnt(0)
	v_mfma_f32_16x16x32_bf16 v[60:63], v[136:139], v[174:177], 0
	v_mfma_f32_16x16x32_bf16 v[56:59], v[150:153], v[174:177], 0
	v_mfma_f32_16x16x32_bf16 v[44:47], v[136:139], v[182:185], 0
	v_mfma_f32_16x16x32_bf16 v[40:43], v[150:153], v[182:185], 0
	v_mfma_f32_16x16x32_bf16 v[28:31], v[136:139], v[190:193], 0
	v_mfma_f32_16x16x32_bf16 v[24:27], v[150:153], v[190:193], 0
	v_mfma_f32_16x16x32_bf16 v[12:15], v[136:139], v[202:205], 0
	v_mfma_f32_16x16x32_bf16 v[8:11], v[150:153], v[202:205], 0
	v_mfma_f32_16x16x32_bf16 v[60:63], v[146:149], v[178:181], v[60:63]
	v_mfma_f32_16x16x32_bf16 v[56:59], v[154:157], v[178:181], v[56:59]
	v_mfma_f32_16x16x32_bf16 v[44:47], v[146:149], v[186:189], v[44:47]
	v_mfma_f32_16x16x32_bf16 v[40:43], v[154:157], v[186:189], v[40:43]
	v_mfma_f32_16x16x32_bf16 v[28:31], v[146:149], v[194:197], v[28:31]
	v_mfma_f32_16x16x32_bf16 v[24:27], v[154:157], v[194:197], v[24:27]
	v_mfma_f32_16x16x32_bf16 v[12:15], v[146:149], v[206:209], v[12:15]
	v_mfma_f32_16x16x32_bf16 v[8:11], v[154:157], v[206:209], v[8:11]
	s_setprio 0
	s_setprio 1
	v_mfma_f32_16x16x32_bf16 v[52:55], v[158:161], v[174:177], 0
	v_mfma_f32_16x16x32_bf16 v[48:51], v[166:169], v[174:177], 0
	v_mfma_f32_16x16x32_bf16 v[36:39], v[158:161], v[182:185], 0
	v_mfma_f32_16x16x32_bf16 v[32:35], v[166:169], v[182:185], 0
	v_mfma_f32_16x16x32_bf16 v[20:23], v[158:161], v[190:193], 0
	v_mfma_f32_16x16x32_bf16 v[16:19], v[166:169], v[190:193], 0
	v_mfma_f32_16x16x32_bf16 v[4:7], v[158:161], v[202:205], 0
	v_mfma_f32_16x16x32_bf16 v[0:3], v[166:169], v[202:205], 0
	v_mfma_f32_16x16x32_bf16 v[52:55], v[162:165], v[178:181], v[52:55]
	v_mfma_f32_16x16x32_bf16 v[48:51], v[170:173], v[178:181], v[48:51]
	v_mfma_f32_16x16x32_bf16 v[36:39], v[162:165], v[186:189], v[36:39]
	v_mfma_f32_16x16x32_bf16 v[32:35], v[170:173], v[186:189], v[32:35]
	v_mfma_f32_16x16x32_bf16 v[20:23], v[162:165], v[194:197], v[20:23]
	v_mfma_f32_16x16x32_bf16 v[16:19], v[170:173], v[194:197], v[16:19]
	v_mfma_f32_16x16x32_bf16 v[4:7], v[162:165], v[206:209], v[4:7]
	v_mfma_f32_16x16x32_bf16 v[0:3], v[170:173], v[206:209], v[0:3]
	s_setprio 0
	s_barrier
	s_add_i32 s58, 0, 0x18000
	v_add_u32_e32 v130, s58, v142
	s_add_i32 s59, 0, 0x1c000
	ds_read_b128 v[136:139], v130
	ds_read_b128 v[146:149], v130 offset:1024
	ds_read_b128 v[150:153], v130 offset:2048
	ds_read_b128 v[154:157], v130 offset:3072
	v_add_u32_e32 v130, s59, v142
	ds_read_b128 v[158:161], v130
	ds_read_b128 v[162:165], v130 offset:1024
	ds_read_b128 v[166:169], v130 offset:2048
	ds_read_b128 v[170:173], v130 offset:3072
	s_mov_b32 m0, s41
	v_lshl_add_u64 v[212:213], v[210:211], 0, s[14:15]
	ds_read_b128 v[174:177], v145 offset:32768
	ds_read_b128 v[178:181], v145 offset:33792
	ds_read_b128 v[182:185], v145 offset:34816
	ds_read_b128 v[186:189], v145 offset:35840
	ds_read_b128 v[190:193], v145 offset:36864
	ds_read_b128 v[194:197], v145 offset:37888
	ds_read_b128 v[202:205], v145 offset:38912
	ds_read_b128 v[206:209], v145 offset:39936
	global_load_lds_dwordx4 v[212:213], off
	v_lshl_add_u64 v[212:213], v[210:211], 0, s[16:17]
	s_mov_b32 m0, s42
	s_nop 0
	global_load_lds_dwordx4 v[212:213], off
	global_load_dword v250, v[214:215], off
	v_lshl_add_u64 v[214:215], v[214:215], 0, s[20:21]
	s_waitcnt vmcnt(10)
	s_waitcnt lgkmcnt(0)
	s_barrier
	s_setprio 1
	s_waitcnt lgkmcnt(0)
	v_mfma_f32_16x16x32_bf16 v[124:127], v[136:139], v[174:177], v[124:127]
	v_mfma_f32_16x16x32_bf16 v[120:123], v[150:153], v[174:177], v[120:123]
	v_mfma_f32_16x16x32_bf16 v[108:111], v[136:139], v[182:185], v[108:111]
	v_mfma_f32_16x16x32_bf16 v[104:107], v[150:153], v[182:185], v[104:107]
	v_mfma_f32_16x16x32_bf16 v[92:95], v[136:139], v[190:193], v[92:95]
	v_mfma_f32_16x16x32_bf16 v[88:91], v[150:153], v[190:193], v[88:91]
	v_mfma_f32_16x16x32_bf16 v[76:79], v[136:139], v[202:205], v[76:79]
	v_mfma_f32_16x16x32_bf16 v[72:75], v[150:153], v[202:205], v[72:75]
	v_mfma_f32_16x16x32_bf16 v[124:127], v[146:149], v[178:181], v[124:127]
	v_mfma_f32_16x16x32_bf16 v[120:123], v[154:157], v[178:181], v[120:123]
	v_mfma_f32_16x16x32_bf16 v[108:111], v[146:149], v[186:189], v[108:111]
	v_mfma_f32_16x16x32_bf16 v[104:107], v[154:157], v[186:189], v[104:107]
	v_mfma_f32_16x16x32_bf16 v[92:95], v[146:149], v[194:197], v[92:95]
	v_mfma_f32_16x16x32_bf16 v[88:91], v[154:157], v[194:197], v[88:91]
	v_mfma_f32_16x16x32_bf16 v[76:79], v[146:149], v[206:209], v[76:79]
	v_mfma_f32_16x16x32_bf16 v[72:75], v[154:157], v[206:209], v[72:75]
	s_setprio 0
	s_setprio 1
	v_mfma_f32_16x16x32_bf16 v[116:119], v[158:161], v[174:177], v[116:119]
	v_mfma_f32_16x16x32_bf16 v[112:115], v[166:169], v[174:177], v[112:115]
	v_mfma_f32_16x16x32_bf16 v[100:103], v[158:161], v[182:185], v[100:103]
	v_mfma_f32_16x16x32_bf16 v[96:99], v[166:169], v[182:185], v[96:99]
	v_mfma_f32_16x16x32_bf16 v[84:87], v[158:161], v[190:193], v[84:87]
	v_mfma_f32_16x16x32_bf16 v[80:83], v[166:169], v[190:193], v[80:83]
	v_mfma_f32_16x16x32_bf16 v[68:71], v[158:161], v[202:205], v[68:71]
	v_mfma_f32_16x16x32_bf16 v[64:67], v[166:169], v[202:205], v[64:67]
	v_mfma_f32_16x16x32_bf16 v[116:119], v[162:165], v[178:181], v[116:119]
	v_mfma_f32_16x16x32_bf16 v[112:115], v[170:173], v[178:181], v[112:115]
	v_mfma_f32_16x16x32_bf16 v[100:103], v[162:165], v[186:189], v[100:103]
	v_mfma_f32_16x16x32_bf16 v[96:99], v[170:173], v[186:189], v[96:99]
	v_mfma_f32_16x16x32_bf16 v[84:87], v[162:165], v[194:197], v[84:87]
	v_mfma_f32_16x16x32_bf16 v[80:83], v[170:173], v[194:197], v[80:83]
	v_mfma_f32_16x16x32_bf16 v[68:71], v[162:165], v[206:209], v[68:71]
	v_mfma_f32_16x16x32_bf16 v[64:67], v[170:173], v[206:209], v[64:67]
	s_setprio 0
	s_barrier
; #define PG8_STAGE(bufoff, gbase, voff) do { _Pragma("unroll") for (int _i = 0; _i < 2; ++_i) \
;         __builtin_amdgcn_global_load_lds((const unsigned*)((const char*)(gbase) + (voff)[_i]), (PG8_LAS unsigned*)(lds + (bufoff) + ldsw + _i * 8192), 16, 0, 0); } while (0)
; #define PG8_LDA(dst, b, h) do { _Pragma("unroll") for (int m = 0; m < 4; ++m) _Pragma("unroll") for (int k = 0; k < 2; ++k) dst[m][k] = *(const PG8_LAS bf16x8*)(lds + PG8_SA(b, h) + aoff + m * 2048 + k * 1024); } while (0)
; #define PG8_LDB(dst, b, h) do { _Pragma("unroll") for (int n = 0; n < 2; ++n) _Pragma("unroll") for (int k = 0; k < 2; ++k) dst[n][k] = *(const PG8_LAS bf16x8*)(lds + PG8_SB(b, h) + boff + n * 2048 + k * 1024); } while (0)
; #define PG8_MMA(ai, bj, At, Bt) do { __builtin_amdgcn_s_setprio(1); _Pragma("unroll") for (int m = 0; m < 4; ++m) _Pragma("unroll") for (int n = 0; n < 2; ++n) _Pragma("unroll") for (int k = 0; k < 2; ++k) \
;         acc[ai][bj][m][n] = __builtin_amdgcn_mfma_f32_16x16x32_bf16(Bt[n][k], At[m][k], acc[ai][bj][m][n], 0, 0, 0); __builtin_amdgcn_s_setprio(0); } while (0)
; #define PG8_WAIT_V(n) asm volatile("s_waitcnt vmcnt(" #n ")" ::: "memory")
; #define PG8_WAIT_L(n) asm volatile("s_waitcnt lgkmcnt(" #n ")" ::: "memory")
; #define PG8_BAR __builtin_amdgcn_s_barrier()
; #define PG8_SCHED __builtin_amdgcn_sched_barrier(0)
; template <class Epi, class Sched, bool ALIGN_EPI = false, bool SP2 = false>
; __device__ __forceinline__ void gemm_phase(PG8_LAS unsigned char* lds, const Gemm g, const Sched& S, const Epi& E) {
;     ...
;         for (int t = 0; t < nt; t += 2) {
;     ...
;             PG8_LDB(B0, 0, 0); PG8_LDB(B1, 0, 1); PG8_SCHED; PG8_LDA(At, 0, 0); PG8_STAGE(PG8_SA(1, 1), a1 + hstep, voffA);
;     ...
;             PG8_LDA(At, 1, 1); PG8_STAGE(PG8_SB(1, 0), b3, voffB); PG8_STAGE(PG8_SB(1, 1), b3 + hstep, voffB); PG8_STAGE(PG8_SA(1, 0), a3, voffA);
;             PG8_WAIT_V(8); PG8_WAIT_L(0); PG8_BAR; PG8_MMA(1, 0, At, B0); PG8_MMA(1, 1, At, B1); PG8_BAR; PG8_SCHED;
	s_add_i32 s58, s58, s38
	v_lshl_add_u64 v[212:213], v[198:199], 0, s[20:21]
	s_mov_b32 m0, s58
	ds_read_b128 v[174:177], v145 offset:49152
	ds_read_b128 v[178:181], v145 offset:50176
	ds_read_b128 v[182:185], v145 offset:51200
	ds_read_b128 v[186:189], v145 offset:52224
	ds_read_b128 v[190:193], v145 offset:53248
	ds_read_b128 v[194:197], v145 offset:54272
	ds_read_b128 v[202:205], v145 offset:55296
	ds_read_b128 v[206:209], v145 offset:56320
	global_load_lds_dwordx4 v[212:213], off
	v_lshl_add_u64 v[212:213], v[198:199], 0, s[22:23]
	s_add_i32 m0, s58, 0x2000
	s_add_i32 s58, s59, s38
	global_load_lds_dwordx4 v[212:213], off
	v_lshl_add_u64 v[212:213], v[198:199], 0, s[24:25]
	s_mov_b32 m0, s58
	v_lshl_add_u64 v[198:199], v[198:199], 0, s[26:27]
	global_load_lds_dwordx4 v[212:213], off
	s_add_i32 m0, s58, 0x2000
	s_nop 0
	global_load_lds_dwordx4 v[198:199], off
	v_lshl_add_u64 v[198:199], v[210:211], 0, s[20:21]
	s_mov_b32 m0, s46
	s_nop 0
	global_load_lds_dwordx4 v[198:199], off
	v_lshl_add_u64 v[198:199], v[210:211], 0, s[22:23]
	s_mov_b32 m0, s47
	s_nop 0
	global_load_lds_dwordx4 v[198:199], off
	s_waitcnt vmcnt(9)
	s_waitcnt lgkmcnt(0)
	s_barrier
	s_setprio 1
	s_waitcnt lgkmcnt(0)
	v_mfma_f32_16x16x32_bf16 v[60:63], v[136:139], v[174:177], v[60:63]
	v_mfma_f32_16x16x32_bf16 v[56:59], v[150:153], v[174:177], v[56:59]
	v_mfma_f32_16x16x32_bf16 v[44:47], v[136:139], v[182:185], v[44:47]
	v_mfma_f32_16x16x32_bf16 v[40:43], v[150:153], v[182:185], v[40:43]
	v_mfma_f32_16x16x32_bf16 v[28:31], v[136:139], v[190:193], v[28:31]
	v_mfma_f32_16x16x32_bf16 v[24:27], v[150:153], v[190:193], v[24:27]
	v_mfma_f32_16x16x32_bf16 v[12:15], v[136:139], v[202:205], v[12:15]
	v_mfma_f32_16x16x32_bf16 v[8:11], v[150:153], v[202:205], v[8:11]
	v_mfma_f32_16x16x32_bf16 v[60:63], v[146:149], v[178:181], v[60:63]
	v_mfma_f32_16x16x32_bf16 v[56:59], v[154:157], v[178:181], v[56:59]
	v_mfma_f32_16x16x32_bf16 v[44:47], v[146:149], v[186:189], v[44:47]
	v_mfma_f32_16x16x32_bf16 v[40:43], v[154:157], v[186:189], v[40:43]
	v_mfma_f32_16x16x32_bf16 v[28:31], v[146:149], v[194:197], v[28:31]
	v_mfma_f32_16x16x32_bf16 v[24:27], v[154:157], v[194:197], v[24:27]
	v_mfma_f32_16x16x32_bf16 v[12:15], v[146:149], v[206:209], v[12:15]
	v_mfma_f32_16x16x32_bf16 v[8:11], v[154:157], v[206:209], v[8:11]
	s_setprio 0
	s_setprio 1
	v_mfma_f32_16x16x32_bf16 v[52:55], v[158:161], v[174:177], v[52:55]
	v_mfma_f32_16x16x32_bf16 v[48:51], v[166:169], v[174:177], v[48:51]
	v_mfma_f32_16x16x32_bf16 v[36:39], v[158:161], v[182:185], v[36:39]
	v_mfma_f32_16x16x32_bf16 v[32:35], v[166:169], v[182:185], v[32:35]
	v_mfma_f32_16x16x32_bf16 v[20:23], v[158:161], v[190:193], v[20:23]
	v_mfma_f32_16x16x32_bf16 v[16:19], v[166:169], v[190:193], v[16:19]
	v_mfma_f32_16x16x32_bf16 v[4:7], v[158:161], v[202:205], v[4:7]
	v_mfma_f32_16x16x32_bf16 v[0:3], v[166:169], v[202:205], v[0:3]
	v_mfma_f32_16x16x32_bf16 v[52:55], v[162:165], v[178:181], v[52:55]
	v_mfma_f32_16x16x32_bf16 v[48:51], v[170:173], v[178:181], v[48:51]
	v_mfma_f32_16x16x32_bf16 v[36:39], v[162:165], v[186:189], v[36:39]
	v_mfma_f32_16x16x32_bf16 v[32:35], v[170:173], v[186:189], v[32:35]
	v_mfma_f32_16x16x32_bf16 v[20:23], v[162:165], v[194:197], v[20:23]
	v_mfma_f32_16x16x32_bf16 v[16:19], v[170:173], v[194:197], v[16:19]
	v_mfma_f32_16x16x32_bf16 v[4:7], v[162:165], v[206:209], v[4:7]
	v_mfma_f32_16x16x32_bf16 v[0:3], v[170:173], v[206:209], v[0:3]
	s_setprio 0
	s_barrier
	s_add_i32 s57, s57, 2
	s_add_u32 s12, s12, 0x8000
	s_addc_u32 s13, s13, 0
	s_add_u32 s36, s36, 0x8000
	s_addc_u32 s37, s37, 0
	s_cmp_gt_u32 s57, 41
	s_cbranch_scc0 .LBB0_1424
.LBB0_1424:
	ds_read_b128 v[136:139], v143
	ds_read_b128 v[146:149], v143 offset:1024
	ds_read_b128 v[150:153], v143 offset:2048
	ds_read_b128 v[154:157], v143 offset:3072
	ds_read_b128 v[158:161], v144
	ds_read_b128 v[162:165], v144 offset:1024
	ds_read_b128 v[166:169], v144 offset:2048
	ds_read_b128 v[170:173], v144 offset:3072
	s_add_u32 s58, s12, 0xfff54000
	s_addc_u32 s59, s13, -1
	s_cmp_eq_u32 s57, 40
	s_cselect_b32 s59, s3, s59
	s_cselect_b32 s58, s2, s58
	s_cselect_b32 s61, s35, s37
	s_cselect_b32 s60, s34, s36
	v_lshl_add_u64 v[198:199], s[12:13], 0, v[128:129]
	s_add_i32 m0, s39, 0xc000
	ds_read_b128 v[174:177], v145
	ds_read_b128 v[178:181], v145 offset:1024
	ds_read_b128 v[182:185], v145 offset:2048
	ds_read_b128 v[186:189], v145 offset:3072
	ds_read_b128 v[190:193], v145 offset:4096
	ds_read_b128 v[194:197], v145 offset:5120
	ds_read_b128 v[202:205], v145 offset:6144
	ds_read_b128 v[206:209], v145 offset:7168
	global_load_lds_dwordx4 v[198:199], off
	v_lshl_add_u64 v[198:199], v[198:199], 0, s[10:11]
	s_add_i32 m0, s39, 0xe000
	s_nop 0
	global_load_lds_dwordx4 v[198:199], off
	global_load_dword v250, v[214:215], off
	v_lshl_add_u64 v[214:215], v[214:215], 0, s[20:21]
	s_waitcnt vmcnt(10)
	s_waitcnt lgkmcnt(0)
	s_barrier
; #define PG8_STAGE(bufoff, gbase, voff) do { _Pragma("unroll") for (int _i = 0; _i < 2; ++_i) \
;         __builtin_amdgcn_global_load_lds((const unsigned*)((const char*)(gbase) + (voff)[_i]), (PG8_LAS unsigned*)(lds + (bufoff) + ldsw + _i * 8192), 16, 0, 0); } while (0)
; #define PG8_LDA(dst, b, h) do { _Pragma("unroll") for (int m = 0; m < 4; ++m) _Pragma("unroll") for (int k = 0; k < 2; ++k) dst[m][k] = *(const PG8_LAS bf16x8*)(lds + PG8_SA(b, h) + aoff + m * 2048 + k * 1024); } while (0)
; #define PG8_LDB(dst, b, h) do { _Pragma("unroll") for (int n = 0; n < 2; ++n) _Pragma("unroll") for (int k = 0; k < 2; ++k) dst[n][k] = *(const PG8_LAS bf16x8*)(lds + PG8_SB(b, h) + boff + n * 2048 + k * 1024); } while (0)
; #define PG8_MMA(ai, bj, At, Bt) do { __builtin_amdgcn_s_setprio(1); _Pragma("unroll") for (int m = 0; m < 4; ++m) _Pragma("unroll") for (int n = 0; n < 2; ++n) _Pragma("unroll") for (int k = 0; k < 2; ++k) \
;         acc[ai][bj][m][n] = __builtin_amdgcn_mfma_f32_16x16x32_bf16(Bt[n][k], At[m][k], acc[ai][bj][m][n], 0, 0, 0); __builtin_amdgcn_s_setprio(0); } while (0)
; #define PG8_WAIT_V(n) asm volatile("s_waitcnt vmcnt(" #n ")" ::: "memory")
; #define PG8_WAIT_L(n) asm volatile("s_waitcnt lgkmcnt(" #n ")" ::: "memory")
; #define PG8_BAR __builtin_amdgcn_s_barrier()
; #define PG8_SCHED __builtin_amdgcn_sched_barrier(0)
; template <class Epi, class Sched, bool ALIGN_EPI = false, bool SP2 = false>
; __device__ __forceinline__ void gemm_phase(PG8_LAS unsigned char* lds, const Gemm g, const Sched& S, const Epi& E) {
;     ...
;             PG8_WAIT_V(8); PG8_WAIT_L(0); PG8_BAR; PG8_MMA(0, 0, At, B0); PG8_MMA(0, 1, At, B1); PG8_BAR; PG8_SCHED;
;             PG8_LDA(At, 0, 1); PG8_STAGE(PG8_SB(0, 0), b2, voffB); PG8_STAGE(PG8_SB(0, 1), b2 + hstep, voffB); PG8_STAGE(PG8_SA(0, 0), a2, voffA);
;             PG8_WAIT_V(8); PG8_WAIT_L(0); PG8_BAR; PG8_MMA(1, 0, At, B0); PG8_MMA(1, 1, At, B1); PG8_BAR; PG8_SCHED;
;             PG8_LDB(B0, 1, 0); PG8_LDB(B1, 1, 1); PG8_SCHED; PG8_LDA(At, 1, 0); PG8_STAGE(PG8_SA(0, 1), a2 + hstep, voffA);
;             PG8_WAIT_V(8); PG8_WAIT_L(0); PG8_BAR; PG8_MMA(0, 0, At, B0); PG8_MMA(0, 1, At, B1); PG8_BAR; PG8_SCHED;
	s_setprio 1
	s_waitcnt lgkmcnt(0)
	v_mfma_f32_16x16x32_bf16 v[124:127], v[136:139], v[174:177], v[124:127]
	v_mfma_f32_16x16x32_bf16 v[120:123], v[150:153], v[174:177], v[120:123]
	v_mfma_f32_16x16x32_bf16 v[108:111], v[136:139], v[182:185], v[108:111]
	v_mfma_f32_16x16x32_bf16 v[104:107], v[150:153], v[182:185], v[104:107]
	v_mfma_f32_16x16x32_bf16 v[92:95], v[136:139], v[190:193], v[92:95]
	v_mfma_f32_16x16x32_bf16 v[88:91], v[150:153], v[190:193], v[88:91]
	v_mfma_f32_16x16x32_bf16 v[76:79], v[136:139], v[202:205], v[76:79]
	v_mfma_f32_16x16x32_bf16 v[72:75], v[150:153], v[202:205], v[72:75]
	v_mfma_f32_16x16x32_bf16 v[124:127], v[146:149], v[178:181], v[124:127]
	v_mfma_f32_16x16x32_bf16 v[120:123], v[154:157], v[178:181], v[120:123]
	v_mfma_f32_16x16x32_bf16 v[108:111], v[146:149], v[186:189], v[108:111]
	v_mfma_f32_16x16x32_bf16 v[104:107], v[154:157], v[186:189], v[104:107]
	v_mfma_f32_16x16x32_bf16 v[92:95], v[146:149], v[194:197], v[92:95]
	v_mfma_f32_16x16x32_bf16 v[88:91], v[154:157], v[194:197], v[88:91]
	v_mfma_f32_16x16x32_bf16 v[76:79], v[146:149], v[206:209], v[76:79]
	v_mfma_f32_16x16x32_bf16 v[72:75], v[154:157], v[206:209], v[72:75]
	s_setprio 0
	s_setprio 1
	v_mfma_f32_16x16x32_bf16 v[116:119], v[158:161], v[174:177], v[116:119]
	v_mfma_f32_16x16x32_bf16 v[112:115], v[166:169], v[174:177], v[112:115]
	v_mfma_f32_16x16x32_bf16 v[100:103], v[158:161], v[182:185], v[100:103]
	v_mfma_f32_16x16x32_bf16 v[96:99], v[166:169], v[182:185], v[96:99]
	v_mfma_f32_16x16x32_bf16 v[84:87], v[158:161], v[190:193], v[84:87]
	v_mfma_f32_16x16x32_bf16 v[80:83], v[166:169], v[190:193], v[80:83]
	v_mfma_f32_16x16x32_bf16 v[68:71], v[158:161], v[202:205], v[68:71]
	v_mfma_f32_16x16x32_bf16 v[64:67], v[166:169], v[202:205], v[64:67]
	v_mfma_f32_16x16x32_bf16 v[116:119], v[162:165], v[178:181], v[116:119]
	v_mfma_f32_16x16x32_bf16 v[112:115], v[170:173], v[178:181], v[112:115]
	v_mfma_f32_16x16x32_bf16 v[100:103], v[162:165], v[186:189], v[100:103]
	v_mfma_f32_16x16x32_bf16 v[96:99], v[170:173], v[186:189], v[96:99]
	v_mfma_f32_16x16x32_bf16 v[84:87], v[162:165], v[194:197], v[84:87]
	v_mfma_f32_16x16x32_bf16 v[80:83], v[170:173], v[194:197], v[80:83]
	v_mfma_f32_16x16x32_bf16 v[68:71], v[162:165], v[206:209], v[68:71]
	v_mfma_f32_16x16x32_bf16 v[64:67], v[170:173], v[206:209], v[64:67]
	s_setprio 0
	s_barrier
	v_lshl_add_u64 v[198:199], s[60:61], 0, v[128:129]
	s_add_i32 s60, s51, s38
	s_mov_b32 m0, s60
	ds_read_b128 v[174:177], v145 offset:16384
	ds_read_b128 v[178:181], v145 offset:17408
	ds_read_b128 v[182:185], v145 offset:18432
	ds_read_b128 v[186:189], v145 offset:19456
	ds_read_b128 v[190:193], v145 offset:20480
	ds_read_b128 v[194:197], v145 offset:21504
	ds_read_b128 v[202:205], v145 offset:22528
	ds_read_b128 v[206:209], v145 offset:23552
	global_load_lds_dwordx4 v[198:199], off
	v_lshl_add_u64 v[210:211], v[198:199], 0, s[10:11]
	s_add_i32 m0, s60, 0x2000
	s_add_i32 s60, s52, s38
	global_load_lds_dwordx4 v[210:211], off
	v_lshl_add_u64 v[210:211], v[198:199], 0, s[14:15]
	s_mov_b32 m0, s60
	s_nop 0
	global_load_lds_dwordx4 v[210:211], off
	v_lshl_add_u64 v[210:211], v[198:199], 0, s[16:17]
	s_add_i32 m0, s60, 0x2000
	s_nop 0
	global_load_lds_dwordx4 v[210:211], off
	v_lshl_add_u64 v[210:211], s[58:59], 0, v[128:129]
	s_mov_b32 m0, s39
	v_lshl_add_u64 v[212:213], v[210:211], 0, s[10:11]
	global_load_lds_dwordx4 v[210:211], off
	s_mov_b32 m0, s40
	s_nop 0
	global_load_lds_dwordx4 v[212:213], off
	s_waitcnt vmcnt(9)
	s_waitcnt lgkmcnt(0)
	s_barrier
	s_setprio 1
	s_waitcnt lgkmcnt(0)
	v_mfma_f32_16x16x32_bf16 v[60:63], v[136:139], v[174:177], v[60:63]
	v_mfma_f32_16x16x32_bf16 v[56:59], v[150:153], v[174:177], v[56:59]
	v_mfma_f32_16x16x32_bf16 v[44:47], v[136:139], v[182:185], v[44:47]
	v_mfma_f32_16x16x32_bf16 v[40:43], v[150:153], v[182:185], v[40:43]
	v_mfma_f32_16x16x32_bf16 v[28:31], v[136:139], v[190:193], v[28:31]
	v_mfma_f32_16x16x32_bf16 v[24:27], v[150:153], v[190:193], v[24:27]
	v_mfma_f32_16x16x32_bf16 v[12:15], v[136:139], v[202:205], v[12:15]
	v_mfma_f32_16x16x32_bf16 v[8:11], v[150:153], v[202:205], v[8:11]
	v_mfma_f32_16x16x32_bf16 v[60:63], v[146:149], v[178:181], v[60:63]
	v_mfma_f32_16x16x32_bf16 v[56:59], v[154:157], v[178:181], v[56:59]
	v_mfma_f32_16x16x32_bf16 v[44:47], v[146:149], v[186:189], v[44:47]
	v_mfma_f32_16x16x32_bf16 v[40:43], v[154:157], v[186:189], v[40:43]
	v_mfma_f32_16x16x32_bf16 v[28:31], v[146:149], v[194:197], v[28:31]
	v_mfma_f32_16x16x32_bf16 v[24:27], v[154:157], v[194:197], v[24:27]
	v_mfma_f32_16x16x32_bf16 v[12:15], v[146:149], v[206:209], v[12:15]
	v_mfma_f32_16x16x32_bf16 v[8:11], v[154:157], v[206:209], v[8:11]
	s_setprio 0
	s_setprio 1
	v_mfma_f32_16x16x32_bf16 v[52:55], v[158:161], v[174:177], v[52:55]
	v_mfma_f32_16x16x32_bf16 v[48:51], v[166:169], v[174:177], v[48:51]
	v_mfma_f32_16x16x32_bf16 v[36:39], v[158:161], v[182:185], v[36:39]
	v_mfma_f32_16x16x32_bf16 v[32:35], v[166:169], v[182:185], v[32:35]
	v_mfma_f32_16x16x32_bf16 v[20:23], v[158:161], v[190:193], v[20:23]
	v_mfma_f32_16x16x32_bf16 v[16:19], v[166:169], v[190:193], v[16:19]
	v_mfma_f32_16x16x32_bf16 v[4:7], v[158:161], v[202:205], v[4:7]
	v_mfma_f32_16x16x32_bf16 v[0:3], v[166:169], v[202:205], v[0:3]
	v_mfma_f32_16x16x32_bf16 v[52:55], v[162:165], v[178:181], v[52:55]
	v_mfma_f32_16x16x32_bf16 v[48:51], v[170:173], v[178:181], v[48:51]
	v_mfma_f32_16x16x32_bf16 v[36:39], v[162:165], v[186:189], v[36:39]
	v_mfma_f32_16x16x32_bf16 v[32:35], v[170:173], v[186:189], v[32:35]
	v_mfma_f32_16x16x32_bf16 v[20:23], v[162:165], v[194:197], v[20:23]
	v_mfma_f32_16x16x32_bf16 v[16:19], v[170:173], v[194:197], v[16:19]
	v_mfma_f32_16x16x32_bf16 v[4:7], v[162:165], v[206:209], v[4:7]
	v_mfma_f32_16x16x32_bf16 v[0:3], v[170:173], v[206:209], v[0:3]
	s_setprio 0
	s_barrier
; #define PG8_STAGE(bufoff, gbase, voff) do { _Pragma("unroll") for (int _i = 0; _i < 2; ++_i) \
;         __builtin_amdgcn_global_load_lds((const unsigned*)((const char*)(gbase) + (voff)[_i]), (PG8_LAS unsigned*)(lds + (bufoff) + ldsw + _i * 8192), 16, 0, 0); } while (0)
; #define PG8_LDA(dst, b, h) do { _Pragma("unroll") for (int m = 0; m < 4; ++m) _Pragma("unroll") for (int k = 0; k < 2; ++k) dst[m][k] = *(const PG8_LAS bf16x8*)(lds + PG8_SA(b, h) + aoff + m * 2048 + k * 1024); } while (0)
; #define PG8_LDB(dst, b, h) do { _Pragma("unroll") for (int n = 0; n < 2; ++n) _Pragma("unroll") for (int k = 0; k < 2; ++k) dst[n][k] = *(const PG8_LAS bf16x8*)(lds + PG8_SB(b, h) + boff + n * 2048 + k * 1024); } while (0)
; #define PG8_MMA(ai, bj, At, Bt) do { __builtin_amdgcn_s_setprio(1); _Pragma("unroll") for (int m = 0; m < 4; ++m) _Pragma("unroll") for (int n = 0; n < 2; ++n) _Pragma("unroll") for (int k = 0; k < 2; ++k) \
;         acc[ai][bj][m][n] = __builtin_amdgcn_mfma_f32_16x16x32_bf16(Bt[n][k], At[m][k], acc[ai][bj][m][n], 0, 0, 0); __builtin_amdgcn_s_setprio(0); } while (0)
; #define PG8_WAIT_V(n) asm volatile("s_waitcnt vmcnt(" #n ")" ::: "memory")
; #define PG8_WAIT_L(n) asm volatile("s_waitcnt lgkmcnt(" #n ")" ::: "memory")
; #define PG8_BAR __builtin_amdgcn_s_barrier()
; #define PG8_SCHED __builtin_amdgcn_sched_barrier(0)
; template <class Epi, class Sched, bool ALIGN_EPI = false, bool SP2 = false>
; __device__ __forceinline__ void gemm_phase(PG8_LAS unsigned char* lds, const Gemm g, const Sched& S, const Epi& E) {
;     ...
;             PG8_LDB(B0, 1, 0); PG8_LDB(B1, 1, 1); PG8_SCHED; PG8_LDA(At, 1, 0); PG8_STAGE(PG8_SA(0, 1), a2 + hstep, voffA);
;             PG8_WAIT_V(8); PG8_WAIT_L(0); PG8_BAR; PG8_MMA(0, 0, At, B0); PG8_MMA(0, 1, At, B1); PG8_BAR; PG8_SCHED;
	s_add_i32 s58, 0, 0x18000
	v_add_u32_e32 v130, s58, v142
	s_add_i32 s59, 0, 0x1c000
	ds_read_b128 v[136:139], v130
	ds_read_b128 v[146:149], v130 offset:1024
	ds_read_b128 v[150:153], v130 offset:2048
	ds_read_b128 v[154:157], v130 offset:3072
	v_add_u32_e32 v130, s59, v142
	ds_read_b128 v[158:161], v130
	ds_read_b128 v[162:165], v130 offset:1024
	ds_read_b128 v[166:169], v130 offset:2048
	ds_read_b128 v[170:173], v130 offset:3072
	s_mov_b32 m0, s41
	v_lshl_add_u64 v[212:213], v[210:211], 0, s[14:15]
	ds_read_b128 v[174:177], v145 offset:32768
	ds_read_b128 v[178:181], v145 offset:33792
	ds_read_b128 v[182:185], v145 offset:34816
	ds_read_b128 v[186:189], v145 offset:35840
	ds_read_b128 v[190:193], v145 offset:36864
	ds_read_b128 v[194:197], v145 offset:37888
	ds_read_b128 v[202:205], v145 offset:38912
	ds_read_b128 v[206:209], v145 offset:39936
	global_load_lds_dwordx4 v[212:213], off
	v_lshl_add_u64 v[212:213], v[210:211], 0, s[16:17]
	s_mov_b32 m0, s42
	s_nop 0
	global_load_lds_dwordx4 v[212:213], off
	global_load_dword v250, v[214:215], off
	v_lshl_add_u64 v[214:215], v[214:215], 0, s[20:21]
	s_waitcnt vmcnt(10)
	s_waitcnt lgkmcnt(0)
	s_barrier
	s_setprio 1
	s_waitcnt lgkmcnt(0)
	v_mfma_f32_16x16x32_bf16 v[124:127], v[136:139], v[174:177], v[124:127]
	v_mfma_f32_16x16x32_bf16 v[120:123], v[150:153], v[174:177], v[120:123]
	v_mfma_f32_16x16x32_bf16 v[108:111], v[136:139], v[182:185], v[108:111]
	v_mfma_f32_16x16x32_bf16 v[104:107], v[150:153], v[182:185], v[104:107]
	v_mfma_f32_16x16x32_bf16 v[92:95], v[136:139], v[190:193], v[92:95]
	v_mfma_f32_16x16x32_bf16 v[88:91], v[150:153], v[190:193], v[88:91]
	v_mfma_f32_16x16x32_bf16 v[76:79], v[136:139], v[202:205], v[76:79]
	v_mfma_f32_16x16x32_bf16 v[72:75], v[150:153], v[202:205], v[72:75]
	v_mfma_f32_16x16x32_bf16 v[124:127], v[146:149], v[178:181], v[124:127]
	v_mfma_f32_16x16x32_bf16 v[120:123], v[154:157], v[178:181], v[120:123]
	v_mfma_f32_16x16x32_bf16 v[108:111], v[146:149], v[186:189], v[108:111]
	v_mfma_f32_16x16x32_bf16 v[104:107], v[154:157], v[186:189], v[104:107]
	v_mfma_f32_16x16x32_bf16 v[92:95], v[146:149], v[194:197], v[92:95]
	v_mfma_f32_16x16x32_bf16 v[88:91], v[154:157], v[194:197], v[88:91]
	v_mfma_f32_16x16x32_bf16 v[76:79], v[146:149], v[206:209], v[76:79]
	v_mfma_f32_16x16x32_bf16 v[72:75], v[154:157], v[206:209], v[72:75]
	s_setprio 0
	s_setprio 1
	v_mfma_f32_16x16x32_bf16 v[116:119], v[158:161], v[174:177], v[116:119]
	v_mfma_f32_16x16x32_bf16 v[112:115], v[166:169], v[174:177], v[112:115]
	v_mfma_f32_16x16x32_bf16 v[100:103], v[158:161], v[182:185], v[100:103]
	v_mfma_f32_16x16x32_bf16 v[96:99], v[166:169], v[182:185], v[96:99]
	v_mfma_f32_16x16x32_bf16 v[84:87], v[158:161], v[190:193], v[84:87]
	v_mfma_f32_16x16x32_bf16 v[80:83], v[166:169], v[190:193], v[80:83]
	v_mfma_f32_16x16x32_bf16 v[68:71], v[158:161], v[202:205], v[68:71]
	v_mfma_f32_16x16x32_bf16 v[64:67], v[166:169], v[202:205], v[64:67]
	v_mfma_f32_16x16x32_bf16 v[116:119], v[162:165], v[178:181], v[116:119]
	v_mfma_f32_16x16x32_bf16 v[112:115], v[170:173], v[178:181], v[112:115]
	v_mfma_f32_16x16x32_bf16 v[100:103], v[162:165], v[186:189], v[100:103]
	v_mfma_f32_16x16x32_bf16 v[96:99], v[170:173], v[186:189], v[96:99]
	v_mfma_f32_16x16x32_bf16 v[84:87], v[162:165], v[194:197], v[84:87]
	v_mfma_f32_16x16x32_bf16 v[80:83], v[170:173], v[194:197], v[80:83]
	v_mfma_f32_16x16x32_bf16 v[68:71], v[162:165], v[206:209], v[68:71]
	v_mfma_f32_16x16x32_bf16 v[64:67], v[170:173], v[206:209], v[64:67]
	s_setprio 0
	s_barrier
; #define PG8_STAGE(bufoff, gbase, voff) do { _Pragma("unroll") for (int _i = 0; _i < 2; ++_i) \
;         __builtin_amdgcn_global_load_lds((const unsigned*)((const char*)(gbase) + (voff)[_i]), (PG8_LAS unsigned*)(lds + (bufoff) + ldsw + _i * 8192), 16, 0, 0); } while (0)
; #define PG8_LDA(dst, b, h) do { _Pragma("unroll") for (int m = 0; m < 4; ++m) _Pragma("unroll") for (int k = 0; k < 2; ++k) dst[m][k] = *(const PG8_LAS bf16x8*)(lds + PG8_SA(b, h) + aoff + m * 2048 + k * 1024); } while (0)
; #define PG8_MMA(ai, bj, At, Bt) do { __builtin_amdgcn_s_setprio(1); _Pragma("unroll") for (int m = 0; m < 4; ++m) _Pragma("unroll") for (int n = 0; n < 2; ++n) _Pragma("unroll") for (int k = 0; k < 2; ++k) \
;         acc[ai][bj][m][n] = __builtin_amdgcn_mfma_f32_16x16x32_bf16(Bt[n][k], At[m][k], acc[ai][bj][m][n], 0, 0, 0); __builtin_amdgcn_s_setprio(0); } while (0)
; #define PG8_WAIT_V(n) asm volatile("s_waitcnt vmcnt(" #n ")" ::: "memory")
; #define PG8_WAIT_L(n) asm volatile("s_waitcnt lgkmcnt(" #n ")" ::: "memory")
; #define PG8_BAR __builtin_amdgcn_s_barrier()
; #define PG8_SCHED __builtin_amdgcn_sched_barrier(0)
; template <class Epi, class Sched, bool ALIGN_EPI = false, bool SP2 = false>
; __device__ __forceinline__ void gemm_phase(PG8_LAS unsigned char* lds, const Gemm g, const Sched& S, const Epi& E) {
;     ...
;         for (int t = 0; t < nt; t += 2) {
;     ...
;             PG8_LDA(At, 1, 1); PG8_STAGE(PG8_SB(1, 0), b3, voffB); PG8_STAGE(PG8_SB(1, 1), b3 + hstep, voffB); PG8_STAGE(PG8_SA(1, 0), a3, voffA);
;             PG8_WAIT_V(8); PG8_WAIT_L(0); PG8_BAR; PG8_MMA(1, 0, At, B0); PG8_MMA(1, 1, At, B1); PG8_BAR; PG8_SCHED;
	s_add_i32 s58, s58, s38
	v_lshl_add_u64 v[212:213], v[198:199], 0, s[20:21]
	s_mov_b32 m0, s58
	ds_read_b128 v[174:177], v145 offset:49152
	ds_read_b128 v[178:181], v145 offset:50176
	ds_read_b128 v[182:185], v145 offset:51200
	ds_read_b128 v[186:189], v145 offset:52224
	ds_read_b128 v[190:193], v145 offset:53248
	ds_read_b128 v[194:197], v145 offset:54272
	ds_read_b128 v[202:205], v145 offset:55296
	ds_read_b128 v[206:209], v145 offset:56320
	global_load_lds_dwordx4 v[212:213], off
	v_lshl_add_u64 v[212:213], v[198:199], 0, s[22:23]
	s_add_i32 m0, s58, 0x2000
	s_add_i32 s58, s59, s38
	global_load_lds_dwordx4 v[212:213], off
	v_lshl_add_u64 v[212:213], v[198:199], 0, s[24:25]
	s_mov_b32 m0, s58
	v_lshl_add_u64 v[198:199], v[198:199], 0, s[26:27]
	global_load_lds_dwordx4 v[212:213], off
	s_add_i32 m0, s58, 0x2000
	s_nop 0
	global_load_lds_dwordx4 v[198:199], off
	v_lshl_add_u64 v[198:199], v[210:211], 0, s[20:21]
	s_mov_b32 m0, s46
	s_nop 0
	global_load_lds_dwordx4 v[198:199], off
	v_lshl_add_u64 v[198:199], v[210:211], 0, s[22:23]
	s_mov_b32 m0, s47
	s_nop 0
	global_load_lds_dwordx4 v[198:199], off
	s_waitcnt vmcnt(9)
	s_waitcnt lgkmcnt(0)
	s_barrier
	s_setprio 1
	s_waitcnt lgkmcnt(0)
	v_mfma_f32_16x16x32_bf16 v[60:63], v[136:139], v[174:177], v[60:63]
	v_mfma_f32_16x16x32_bf16 v[56:59], v[150:153], v[174:177], v[56:59]
	v_mfma_f32_16x16x32_bf16 v[44:47], v[136:139], v[182:185], v[44:47]
	v_mfma_f32_16x16x32_bf16 v[40:43], v[150:153], v[182:185], v[40:43]
	v_mfma_f32_16x16x32_bf16 v[28:31], v[136:139], v[190:193], v[28:31]
	v_mfma_f32_16x16x32_bf16 v[24:27], v[150:153], v[190:193], v[24:27]
	v_mfma_f32_16x16x32_bf16 v[12:15], v[136:139], v[202:205], v[12:15]
	v_mfma_f32_16x16x32_bf16 v[8:11], v[150:153], v[202:205], v[8:11]
	v_mfma_f32_16x16x32_bf16 v[60:63], v[146:149], v[178:181], v[60:63]
	v_mfma_f32_16x16x32_bf16 v[56:59], v[154:157], v[178:181], v[56:59]
	v_mfma_f32_16x16x32_bf16 v[44:47], v[146:149], v[186:189], v[44:47]
	v_mfma_f32_16x16x32_bf16 v[40:43], v[154:157], v[186:189], v[40:43]
	v_mfma_f32_16x16x32_bf16 v[28:31], v[146:149], v[194:197], v[28:31]
	v_mfma_f32_16x16x32_bf16 v[24:27], v[154:157], v[194:197], v[24:27]
	v_mfma_f32_16x16x32_bf16 v[12:15], v[146:149], v[206:209], v[12:15]
	v_mfma_f32_16x16x32_bf16 v[8:11], v[154:157], v[206:209], v[8:11]
	s_setprio 0
	s_setprio 1
	v_mfma_f32_16x16x32_bf16 v[52:55], v[158:161], v[174:177], v[52:55]
	v_mfma_f32_16x16x32_bf16 v[48:51], v[166:169], v[174:177], v[48:51]
	v_mfma_f32_16x16x32_bf16 v[36:39], v[158:161], v[182:185], v[36:39]
	v_mfma_f32_16x16x32_bf16 v[32:35], v[166:169], v[182:185], v[32:35]
	v_mfma_f32_16x16x32_bf16 v[20:23], v[158:161], v[190:193], v[20:23]
	v_mfma_f32_16x16x32_bf16 v[16:19], v[166:169], v[190:193], v[16:19]
	v_mfma_f32_16x16x32_bf16 v[4:7], v[158:161], v[202:205], v[4:7]
	v_mfma_f32_16x16x32_bf16 v[0:3], v[166:169], v[202:205], v[0:3]
	v_mfma_f32_16x16x32_bf16 v[52:55], v[162:165], v[178:181], v[52:55]
	v_mfma_f32_16x16x32_bf16 v[48:51], v[170:173], v[178:181], v[48:51]
	v_mfma_f32_16x16x32_bf16 v[36:39], v[162:165], v[186:189], v[36:39]
	v_mfma_f32_16x16x32_bf16 v[32:35], v[170:173], v[186:189], v[32:35]
	v_mfma_f32_16x16x32_bf16 v[20:23], v[162:165], v[194:197], v[20:23]
	v_mfma_f32_16x16x32_bf16 v[16:19], v[170:173], v[194:197], v[16:19]
	v_mfma_f32_16x16x32_bf16 v[4:7], v[162:165], v[206:209], v[4:7]
	v_mfma_f32_16x16x32_bf16 v[0:3], v[170:173], v[206:209], v[0:3]
	s_setprio 0
	s_barrier
	s_add_i32 s57, s57, 2
	s_add_u32 s12, s12, 0x8000
	s_addc_u32 s13, s13, 0
	s_add_u32 s36, s36, 0x8000
	s_addc_u32 s37, s37, 0
	s_cmp_gt_u32 s57, 41
	s_cbranch_scc0 .LBB0_1424
	s_and_b64 vcc, exec, s[28:29]
	s_cbranch_vccz .LBB0_1427
	s_barrier
